# LRU gate-weight loads: flat_load_dword -> global_load_dword (256 sites)
# speedup vs baseline: 1.0770x; 1.0025x over previous
; __device__ __forceinline__ unsigned cvt_pk_bf16(float lo, float hi) { f32x2_t v = {lo, hi}; bf2_t r = __builtin_convertvector(v, bf2_t); return __builtin_bit_cast(unsigned, r); }
; template <bool FINAL>
; __device__ __forceinline__ void lru_item(const Ctx& C, int l, int item) {
;     ...
;     bf16x8 Bw[2][4][2];
; #pragma unroll
;         for (int ty = 0; ty < 2; ++ty)
; #pragma unroll
;             for (int ks = 0; ks < 2; ++ks) {
;                 const float* wp = (ty ? C.P->in[9] : C.P->in[7]) + ((size_t)((l * 2 + z) * 4 + n) * 64 + 32 * ks + 8 * quad) * 64 + fr;
;                 asm volatile("" : "+v"(wp));
;                 float f[4][8];
; #pragma unroll
;                 for (int dt = 0; dt < 4; ++dt)
; #pragma unroll
;                     for (int e = 0; e < 8; ++e) f[dt][e] = wp[e * 64 + 16 * dt];
; #pragma unroll
;                 for (int dt = 0; dt < 4; ++dt) {
;                     union { bf16x8 v; unsigned u[4]; } t_; t_.u[0] = cvt_pk_bf16(f[dt][0], f[dt][1]); t_.u[1] = cvt_pk_bf16(f[dt][2], f[dt][3]); t_.u[2] = cvt_pk_bf16(f[dt][4], f[dt][5]); t_.u[3] = cvt_pk_bf16(f[dt][6], f[dt][7]); Bw[ty][dt][ks] = t_.v; }
;                 asm volatile("" ::: "memory");
;             }
.LBB0_435:
	v_mov_b64_e32 v[0:1], v[78:79]
	global_load_dword v6, v[0:1], off
	global_load_dword v9, v[0:1], off offset:256
	global_load_dword v7, v[0:1], off offset:64
	global_load_dword v10, v[0:1], off offset:320
	global_load_dword v8, v[0:1], off offset:128
	global_load_dword v11, v[0:1], off offset:384
	global_load_dword v12, v[0:1], off offset:448
	global_load_dword v13, v[0:1], off offset:192
	global_load_dword v28, v[0:1], off offset:512
	global_load_dword v34, v[0:1], off offset:768
	global_load_dword v20, v[0:1], off offset:576
	global_load_dword v21, v[0:1], off offset:832
	global_load_dword v16, v[0:1], off offset:640
	global_load_dword v17, v[0:1], off offset:896
	global_load_dword v14, v[0:1], off offset:960
	global_load_dword v15, v[0:1], off offset:704
	global_load_dword v40, v[0:1], off offset:1024
	global_load_dword v42, v[0:1], off offset:1280
	global_load_dword v36, v[0:1], off offset:1088
	global_load_dword v37, v[0:1], off offset:1344
	global_load_dword v22, v[0:1], off offset:1152
	global_load_dword v23, v[0:1], off offset:1408
	global_load_dword v18, v[0:1], off offset:1472
	global_load_dword v19, v[0:1], off offset:1216
	global_load_dword v48, v[0:1], off offset:1536
	global_load_dword v50, v[0:1], off offset:1792
	global_load_dword v44, v[0:1], off offset:1600
	global_load_dword v45, v[0:1], off offset:1856
	global_load_dword v38, v[0:1], off offset:1664
	global_load_dword v39, v[0:1], off offset:1920
	global_load_dword v24, v[0:1], off offset:1984
	global_load_dword v29, v[0:1], off offset:1728
	v_mov_b64_e32 v[0:1], v[80:81]
	global_load_dword v25, v[0:1], off
	global_load_dword v30, v[0:1], off offset:256
	global_load_dword v26, v[0:1], off offset:64
	global_load_dword v31, v[0:1], off offset:320
	global_load_dword v27, v[0:1], off offset:128
	global_load_dword v32, v[0:1], off offset:384
	global_load_dword v33, v[0:1], off offset:448
	global_load_dword v35, v[0:1], off offset:192
	global_load_dword v60, v[0:1], off offset:512
	global_load_dword v68, v[0:1], off offset:768
	global_load_dword v52, v[0:1], off offset:576
	global_load_dword v53, v[0:1], off offset:832
	global_load_dword v46, v[0:1], off offset:640
	global_load_dword v47, v[0:1], off offset:896
	global_load_dword v41, v[0:1], off offset:960
	global_load_dword v43, v[0:1], off offset:704
	global_load_dword v74, v[0:1], off offset:1024
	global_load_dword v76, v[0:1], off offset:1280
	global_load_dword v70, v[0:1], off offset:1088
	global_load_dword v71, v[0:1], off offset:1344
	global_load_dword v54, v[0:1], off offset:1152
	global_load_dword v55, v[0:1], off offset:1408
	global_load_dword v49, v[0:1], off offset:1472
	global_load_dword v51, v[0:1], off offset:1216
	global_load_dword v102, v[0:1], off offset:1536
	global_load_dword v104, v[0:1], off offset:1792
	global_load_dword v98, v[0:1], off offset:1600
	global_load_dword v99, v[0:1], off offset:1856
	global_load_dword v72, v[0:1], off offset:1664
	global_load_dword v73, v[0:1], off offset:1920
	global_load_dword v56, v[0:1], off offset:1984
	global_load_dword v61, v[0:1], off offset:1728
	v_mov_b64_e32 v[0:1], v[82:83]
	global_load_dword v57, v[0:1], off
	global_load_dword v62, v[0:1], off offset:256
	global_load_dword v58, v[0:1], off offset:64
	global_load_dword v63, v[0:1], off offset:320
	global_load_dword v59, v[0:1], off offset:128
	global_load_dword v66, v[0:1], off offset:384
	global_load_dword v67, v[0:1], off offset:448
	global_load_dword v69, v[0:1], off offset:192
	global_load_dword v174, v[0:1], off offset:512
	global_load_dword v194, v[0:1], off offset:768
	global_load_dword v166, v[0:1], off offset:576
	global_load_dword v167, v[0:1], off offset:832
	global_load_dword v100, v[0:1], off offset:640
	global_load_dword v101, v[0:1], off offset:896
	global_load_dword v75, v[0:1], off offset:960
	global_load_dword v77, v[0:1], off offset:704
	global_load_dword v200, v[0:1], off offset:1024
	global_load_dword v202, v[0:1], off offset:1280
	global_load_dword v196, v[0:1], off offset:1088
	global_load_dword v197, v[0:1], off offset:1344
	global_load_dword v168, v[0:1], off offset:1152
	global_load_dword v169, v[0:1], off offset:1408
	global_load_dword v103, v[0:1], off offset:1472
	global_load_dword v105, v[0:1], off offset:1216
	global_load_dword v208, v[0:1], off offset:1536
	global_load_dword v210, v[0:1], off offset:1792
	global_load_dword v204, v[0:1], off offset:1600
	global_load_dword v205, v[0:1], off offset:1856
	global_load_dword v198, v[0:1], off offset:1664
	global_load_dword v199, v[0:1], off offset:1920
	global_load_dword v170, v[0:1], off offset:1984
	global_load_dword v175, v[0:1], off offset:1728
	v_mov_b64_e32 v[0:1], v[84:85]
	global_load_dword v171, v[0:1], off
	global_load_dword v176, v[0:1], off offset:256
	global_load_dword v172, v[0:1], off offset:64
	global_load_dword v177, v[0:1], off offset:320
	global_load_dword v173, v[0:1], off offset:128
	global_load_dword v192, v[0:1], off offset:384
	global_load_dword v193, v[0:1], off offset:448
	global_load_dword v195, v[0:1], off offset:192
	global_load_dword v229, v[0:1], off offset:512
	global_load_dword v231, v[0:1], off offset:768
	global_load_dword v212, v[0:1], off offset:576
	global_load_dword v213, v[0:1], off offset:832
	global_load_dword v206, v[0:1], off offset:640
	global_load_dword v207, v[0:1], off offset:896
	global_load_dword v201, v[0:1], off offset:960
	global_load_dword v203, v[0:1], off offset:704
	global_load_dword v236, v[0:1], off offset:1024
	global_load_dword v237, v[0:1], off offset:1280
	global_load_dword v232, v[0:1], off offset:1088
	global_load_dword v233, v[0:1], off offset:1344
; __device__ __forceinline__ bf16_t f2bf(float f) { return (bf16_t)(cvt_pk_bf16(f, 0.f) & 0xffffu); }
; __device__ __forceinline__ float bf2f(bf16_t b) { return __uint_as_float(((unsigned)b) << 16); }
; template <bool FINAL>
; __device__ __forceinline__ void lru_item(const Ctx& C, int l, int item) {
;     ...
;     {
;         int ch = tid & 255; asm volatile("" : "+v"(ch)); const int hf = tid >> 8;
;         const float w0 = C.P->in[5][(l * 4 + 0) * 256 + ch], w1 = C.P->in[5][(l * 4 + 1) * 256 + ch], w2 = C.P->in[5][(l * 4 + 2) * 256 + ch], w3 = C.P->in[5][(l * 4 + 3) * 256 + ch], cb = C.P->in[6][l * 256 + ch];
;         const int tl0 = hf * 32, t0 = c * 64 + tl0;
;         const bf16_t* colp = pb + (size_t)(b * SEQ) * 512 + ch;
;         float xm2 = (t0 - 2 >= 0) ? bf2f(colp[(size_t)(t0 - 2) * 512]) : 0.f, xm1 = (t0 - 1 >= 0) ? bf2f(colp[(size_t)(t0 - 1) * 512]) : 0.f, x0 = bf2f(colp[(size_t)t0 * 512]);
; #pragma unroll 1
;         for (int k8 = 0; k8 < 4; ++k8) { float xn[8];
; #pragma unroll
;             for (int k = 0; k < 8; ++k) { const int t = t0 + k8 * 8 + k + 1; xn[k] = (t < SEQ) ? bf2f(colp[(size_t)t * 512]) : 0.f; }
; #pragma unroll
;             for (int k = 0; k < 8; ++k) { xc[(tl0 + k8 * 8 + k) * XCP + ch] = f2bf(cb + w0 * xm2 + w1 * xm1 + w2 * x0 + w3 * xn[k]); xm2 = xm1; xm1 = x0; x0 = xn[k]; } }
	global_load_dword v214, v[0:1], off offset:1152
	global_load_dword v215, v[0:1], off offset:1408
	global_load_dword v209, v[0:1], off offset:1472
	global_load_dword v211, v[0:1], off offset:1216
	global_load_dword v240, v[0:1], off offset:1536
	global_load_dword v241, v[0:1], off offset:1792
	global_load_dword v238, v[0:1], off offset:1600
	global_load_dword v239, v[0:1], off offset:1856
	global_load_dword v234, v[0:1], off offset:1664
	global_load_dword v235, v[0:1], off offset:1920
	global_load_dword v228, v[0:1], off offset:1984
	global_load_dword v230, v[0:1], off offset:1728
	v_mov_b32_e32 v4, v95
	v_readlane_b32 s0, v254, 63
	v_readlane_b32 s78, v251, 14
	v_readlane_b32 s79, v251, 15
	v_readlane_b32 s80, v251, 16
	v_readlane_b32 s81, v251, 17
	v_add_u32_e32 v0, s0, v4
	v_ashrrev_i32_e32 v1, 31, v0
	v_lshl_add_u64 v[2:3], v[0:1], 2, s[78:79]
	v_add_u32_e32 v0, s40, v0
	global_load_dword v155, v[2:3], off
	global_load_dword v156, v[2:3], off offset:1024
	global_load_dword v157, v[2:3], off offset:2048
	global_load_dword v158, v[2:3], off offset:3072
	v_ashrrev_i32_e32 v1, 31, v0
	v_lshl_add_u64 v[0:1], v[0:1], 2, s[80:81]
	global_load_dword v159, v[0:1], off
	s_lshl_b32 s0, s17, 6
	s_and_b32 s0, s0, 0xfffff000
	s_ashr_i32 s1, s0, 31
	s_and_b32 s18, s17, 63
	s_lshl_b64 s[0:1], s[0:1], 10
	s_add_u32 s0, s12, s0
	s_addc_u32 s1, s13, s1
	v_lshl_add_u32 v183, s18, 6, v97
	v_ashrrev_i32_e32 v5, 31, v4
	v_lshl_add_u64 v[0:1], v[4:5], 1, s[0:1]
	v_lshl_add_u32 v64, v4, 1, v135
	s_mov_b64 s[22:23], 0x2000
	v_add_u32_e32 v2, 2, v183
	v_mov_b32_e32 v3, 0
	v_lshlrev_b64 v[2:3], 10, v[2:3]
	v_lshl_add_u64 v[2:3], v[2:3], 0, v[0:1]
	global_load_ushort v4, v[2:3], off offset:-4096
	global_load_ushort v5, v[2:3], off offset:-3072
	global_load_ushort v160, v[2:3], off offset:-2048
	global_load_ushort v161, v[2:3], off offset:-1024
	global_load_ushort v162, v[2:3], off
	global_load_ushort v163, v[2:3], off offset:1024
	global_load_ushort v164, v[2:3], off offset:2048
	global_load_ushort v165, v[2:3], off offset:3072
	v_lshl_add_u64 v[2:3], v[2:3], 0, s[22:23]
	global_load_ushort v178, v[2:3], off offset:-4096
	global_load_ushort v179, v[2:3], off offset:-3072
	global_load_ushort v180, v[2:3], off offset:-2048
	global_load_ushort v181, v[2:3], off offset:-1024
	global_load_ushort v188, v[2:3], off
	global_load_ushort v189, v[2:3], off offset:1024
	global_load_ushort v190, v[2:3], off offset:2048
	global_load_ushort v191, v[2:3], off offset:3072
	v_lshl_add_u64 v[2:3], v[2:3], 0, s[22:23]
	global_load_ushort v223, v[2:3], off offset:-4096
	global_load_ushort v242, v[2:3], off offset:-3072
	global_load_ushort v243, v[2:3], off offset:-2048
	s_movk_i32 s19, 0xfe0
	v_cmp_eq_u32_e32 vcc, 0, v183
	v_cmp_eq_u32_e64 s[0:1], s19, v183
	s_waitcnt vmcnt(0)
	v_cndmask_b32_e64 v4, v4, 0, vcc
	v_cndmask_b32_e64 v5, v5, 0, vcc
	v_lshlrev_b32_e32 v4, 16, v4
	v_lshlrev_b32_e32 v5, 16, v5
	v_lshlrev_b32_e32 v160, 16, v160
	v_lshlrev_b32_e32 v161, 16, v161
	v_lshlrev_b32_e32 v162, 16, v162
	v_lshlrev_b32_e32 v163, 16, v163
	v_lshlrev_b32_e32 v164, 16, v164
	v_lshlrev_b32_e32 v165, 16, v165
	v_lshlrev_b32_e32 v178, 16, v178
	v_lshlrev_b32_e32 v179, 16, v179
	v_lshlrev_b32_e32 v180, 16, v180
	v_lshlrev_b32_e32 v181, 16, v181
	v_lshlrev_b32_e32 v188, 16, v188
	v_lshlrev_b32_e32 v189, 16, v189
	v_lshlrev_b32_e32 v190, 16, v190
	v_lshlrev_b32_e32 v191, 16, v191
	v_lshlrev_b32_e32 v223, 16, v223
	v_lshlrev_b32_e32 v242, 16, v242
	v_lshlrev_b32_e32 v243, 16, v243
	v_fma_f32 v0, v155, v4, v159
	v_fmac_f32_e32 v0, v156, v5
	v_fmac_f32_e32 v0, v157, v160
	v_fmac_f32_e32 v0, v158, v161
	v_cvt_pk_bf16_f32 v0, v0, v0
	ds_write_b16 v64, v0
	v_fma_f32 v1, v155, v5, v159
	v_fmac_f32_e32 v1, v156, v160
	v_fmac_f32_e32 v1, v157, v161
	v_fmac_f32_e32 v1, v158, v162
	v_cvt_pk_bf16_f32 v1, v1, v1
	ds_write_b16 v64, v1 offset:528
	v_fma_f32 v0, v155, v160, v159
	v_fmac_f32_e32 v0, v156, v161
	v_fmac_f32_e32 v0, v157, v162
	v_fmac_f32_e32 v0, v158, v163
	v_cvt_pk_bf16_f32 v0, v0, v0
	ds_write_b16 v64, v0 offset:1056
	v_fma_f32 v1, v155, v161, v159
	v_fmac_f32_e32 v1, v156, v162
	v_fmac_f32_e32 v1, v157, v163
	v_fmac_f32_e32 v1, v158, v164
	v_cvt_pk_bf16_f32 v1, v1, v1
	ds_write_b16 v64, v1 offset:1584
	v_fma_f32 v0, v155, v162, v159
	v_fmac_f32_e32 v0, v156, v163
	v_fmac_f32_e32 v0, v157, v164
	v_fmac_f32_e32 v0, v158, v165
	v_cvt_pk_bf16_f32 v0, v0, v0
	ds_write_b16 v64, v0 offset:2112
	v_fma_f32 v1, v155, v163, v159
	v_fmac_f32_e32 v1, v156, v164
	v_fmac_f32_e32 v1, v157, v165
	v_fmac_f32_e32 v1, v158, v178
	v_cvt_pk_bf16_f32 v1, v1, v1
	ds_write_b16 v64, v1 offset:2640
	v_fma_f32 v0, v155, v164, v159
	v_fmac_f32_e32 v0, v156, v165
	v_fmac_f32_e32 v0, v157, v178
	v_fmac_f32_e32 v0, v158, v179
	v_cvt_pk_bf16_f32 v0, v0, v0
	ds_write_b16 v64, v0 offset:3168
	v_fma_f32 v1, v155, v165, v159
	v_fmac_f32_e32 v1, v156, v178
	v_fmac_f32_e32 v1, v157, v179
	v_fmac_f32_e32 v1, v158, v180
	v_cvt_pk_bf16_f32 v1, v1, v1
	ds_write_b16 v64, v1 offset:3696
	v_fma_f32 v0, v155, v178, v159
	v_fmac_f32_e32 v0, v156, v179
	v_fmac_f32_e32 v0, v157, v180
	v_fmac_f32_e32 v0, v158, v181
	v_cvt_pk_bf16_f32 v0, v0, v0
	ds_write_b16 v64, v0 offset:4224
	v_fma_f32 v1, v155, v179, v159
	v_fmac_f32_e32 v1, v156, v180
	v_fmac_f32_e32 v1, v157, v181
	v_fmac_f32_e32 v1, v158, v188
	v_cvt_pk_bf16_f32 v1, v1, v1
	ds_write_b16 v64, v1 offset:4752
	v_fma_f32 v0, v155, v180, v159
	v_fmac_f32_e32 v0, v156, v181
	v_fmac_f32_e32 v0, v157, v188
	v_fmac_f32_e32 v0, v158, v189
; __device__ __forceinline__ bf16_t f2bf(float f) { return (bf16_t)(cvt_pk_bf16(f, 0.f) & 0xffffu); }
; __device__ __forceinline__ float bf2f(bf16_t b) { return __uint_as_float(((unsigned)b) << 16); }
; template <bool FINAL>
; __device__ __forceinline__ void lru_item(const Ctx& C, int l, int item) {
;     ...
; #pragma unroll 1
;         for (int k8 = 0; k8 < 4; ++k8) { float xn[8];
; #pragma unroll
;             for (int k = 0; k < 8; ++k) { const int t = t0 + k8 * 8 + k + 1; xn[k] = (t < SEQ) ? bf2f(colp[(size_t)t * 512]) : 0.f; }
; #pragma unroll
;             for (int k = 0; k < 8; ++k) { xc[(tl0 + k8 * 8 + k) * XCP + ch] = f2bf(cb + w0 * xm2 + w1 * xm1 + w2 * x0 + w3 * xn[k]); xm2 = xm1; xm1 = x0; x0 = xn[k]; } }
	v_cvt_pk_bf16_f32 v0, v0, v0
	ds_write_b16 v64, v0 offset:5280
	v_fma_f32 v1, v155, v181, v159
	v_fmac_f32_e32 v1, v156, v188
	v_fmac_f32_e32 v1, v157, v189
	v_fmac_f32_e32 v1, v158, v190
	v_cvt_pk_bf16_f32 v1, v1, v1
	ds_write_b16 v64, v1 offset:5808
	v_fma_f32 v0, v155, v188, v159
	v_fmac_f32_e32 v0, v156, v189
	v_fmac_f32_e32 v0, v157, v190
	v_fmac_f32_e32 v0, v158, v191
	v_cvt_pk_bf16_f32 v0, v0, v0
	ds_write_b16 v64, v0 offset:6336
	v_fma_f32 v1, v155, v189, v159
	v_fmac_f32_e32 v1, v156, v190
	v_fmac_f32_e32 v1, v157, v191
	v_fmac_f32_e32 v1, v158, v223
	v_cvt_pk_bf16_f32 v1, v1, v1
	ds_write_b16 v64, v1 offset:6864
	v_fma_f32 v0, v155, v190, v159
	v_fmac_f32_e32 v0, v156, v191
	v_fmac_f32_e32 v0, v157, v223
	v_fmac_f32_e32 v0, v158, v242
	v_cvt_pk_bf16_f32 v0, v0, v0
	ds_write_b16 v64, v0 offset:7392
	v_fma_f32 v1, v155, v191, v159
	v_fmac_f32_e32 v1, v156, v223
	v_fmac_f32_e32 v1, v157, v242
	v_fmac_f32_e32 v1, v158, v243
	v_cvt_pk_bf16_f32 v1, v1, v1
	ds_write_b16 v64, v1 offset:7920
	global_load_ushort v4, v[2:3], off offset:-1024
	global_load_ushort v5, v[2:3], off
	global_load_ushort v160, v[2:3], off offset:1024
	global_load_ushort v161, v[2:3], off offset:2048
	global_load_ushort v162, v[2:3], off offset:3072
	v_lshl_add_u64 v[2:3], v[2:3], 0, s[22:23]
	global_load_ushort v163, v[2:3], off offset:-4096
	global_load_ushort v164, v[2:3], off offset:-3072
	global_load_ushort v165, v[2:3], off offset:-2048
	global_load_ushort v178, v[2:3], off offset:-1024
	global_load_ushort v179, v[2:3], off
	global_load_ushort v180, v[2:3], off offset:1024
	global_load_ushort v181, v[2:3], off offset:2048
	global_load_ushort v188, v[2:3], off offset:3072
	v_lshl_add_u64 v[2:3], v[2:3], 0, s[22:23]
	global_load_ushort v189, v[2:3], off offset:-4096
	global_load_ushort v190, v[2:3], off offset:-3072
	global_load_ushort v191, v[2:3], off offset:-2048
	s_waitcnt vmcnt(0)
	v_cndmask_b32_e64 v191, v191, 0, s[0:1]
	v_lshlrev_b32_e32 v4, 16, v4
	v_lshlrev_b32_e32 v5, 16, v5
	v_lshlrev_b32_e32 v160, 16, v160
	v_lshlrev_b32_e32 v161, 16, v161
	v_lshlrev_b32_e32 v162, 16, v162
	v_lshlrev_b32_e32 v163, 16, v163
	v_lshlrev_b32_e32 v164, 16, v164
	v_lshlrev_b32_e32 v165, 16, v165
	v_lshlrev_b32_e32 v178, 16, v178
	v_lshlrev_b32_e32 v179, 16, v179
	v_lshlrev_b32_e32 v180, 16, v180
	v_lshlrev_b32_e32 v181, 16, v181
	v_lshlrev_b32_e32 v188, 16, v188
	v_lshlrev_b32_e32 v189, 16, v189
	v_lshlrev_b32_e32 v190, 16, v190
	v_lshlrev_b32_e32 v191, 16, v191
	v_fma_f32 v0, v155, v223, v159
	v_fmac_f32_e32 v0, v156, v242
	v_fmac_f32_e32 v0, v157, v243
	v_fmac_f32_e32 v0, v158, v4
	v_cvt_pk_bf16_f32 v0, v0, v0
	ds_write_b16 v64, v0 offset:8448
	v_fma_f32 v1, v155, v242, v159
	v_fmac_f32_e32 v1, v156, v243
	v_fmac_f32_e32 v1, v157, v4
	v_fmac_f32_e32 v1, v158, v5
	v_cvt_pk_bf16_f32 v1, v1, v1
	ds_write_b16 v64, v1 offset:8976
	v_fma_f32 v0, v155, v243, v159
	v_fmac_f32_e32 v0, v156, v4
	v_fmac_f32_e32 v0, v157, v5
	v_fmac_f32_e32 v0, v158, v160
	v_cvt_pk_bf16_f32 v0, v0, v0
	ds_write_b16 v64, v0 offset:9504
	v_fma_f32 v1, v155, v4, v159
	v_fmac_f32_e32 v1, v156, v5
	v_fmac_f32_e32 v1, v157, v160
	v_fmac_f32_e32 v1, v158, v161
	v_cvt_pk_bf16_f32 v1, v1, v1
	ds_write_b16 v64, v1 offset:10032
	v_fma_f32 v0, v155, v5, v159
	v_fmac_f32_e32 v0, v156, v160
	v_fmac_f32_e32 v0, v157, v161
	v_fmac_f32_e32 v0, v158, v162
	v_cvt_pk_bf16_f32 v0, v0, v0
	ds_write_b16 v64, v0 offset:10560
	v_fma_f32 v1, v155, v160, v159
	v_fmac_f32_e32 v1, v156, v161
	v_fmac_f32_e32 v1, v157, v162
	v_fmac_f32_e32 v1, v158, v163
	v_cvt_pk_bf16_f32 v1, v1, v1
	ds_write_b16 v64, v1 offset:11088
	v_fma_f32 v0, v155, v161, v159
	v_fmac_f32_e32 v0, v156, v162
	v_fmac_f32_e32 v0, v157, v163
	v_fmac_f32_e32 v0, v158, v164
	v_cvt_pk_bf16_f32 v0, v0, v0
	ds_write_b16 v64, v0 offset:11616
	v_fma_f32 v1, v155, v162, v159
	v_fmac_f32_e32 v1, v156, v163
	v_fmac_f32_e32 v1, v157, v164
	v_fmac_f32_e32 v1, v158, v165
	v_cvt_pk_bf16_f32 v1, v1, v1
	ds_write_b16 v64, v1 offset:12144
	v_fma_f32 v0, v155, v163, v159
	v_fmac_f32_e32 v0, v156, v164
	v_fmac_f32_e32 v0, v157, v165
	v_fmac_f32_e32 v0, v158, v178
	v_cvt_pk_bf16_f32 v0, v0, v0
	ds_write_b16 v64, v0 offset:12672
	v_fma_f32 v1, v155, v164, v159
	v_fmac_f32_e32 v1, v156, v165
	v_fmac_f32_e32 v1, v157, v178
	v_fmac_f32_e32 v1, v158, v179
	v_cvt_pk_bf16_f32 v1, v1, v1
	ds_write_b16 v64, v1 offset:13200
	v_fma_f32 v0, v155, v165, v159
	v_fmac_f32_e32 v0, v156, v178
	v_fmac_f32_e32 v0, v157, v179
	v_fmac_f32_e32 v0, v158, v180
	v_cvt_pk_bf16_f32 v0, v0, v0
	ds_write_b16 v64, v0 offset:13728
	v_fma_f32 v1, v155, v178, v159
	v_fmac_f32_e32 v1, v156, v179
	v_fmac_f32_e32 v1, v157, v180
	v_fmac_f32_e32 v1, v158, v181
	v_cvt_pk_bf16_f32 v1, v1, v1
	ds_write_b16 v64, v1 offset:14256
	v_fma_f32 v0, v155, v179, v159
	v_fmac_f32_e32 v0, v156, v180
	v_fmac_f32_e32 v0, v157, v181
	v_fmac_f32_e32 v0, v158, v188
	v_cvt_pk_bf16_f32 v0, v0, v0
	ds_write_b16 v64, v0 offset:14784
	v_fma_f32 v1, v155, v180, v159
	v_fmac_f32_e32 v1, v156, v181
	v_fmac_f32_e32 v1, v157, v188
	v_fmac_f32_e32 v1, v158, v189
	v_cvt_pk_bf16_f32 v1, v1, v1
	ds_write_b16 v64, v1 offset:15312
	v_fma_f32 v0, v155, v181, v159
	v_fmac_f32_e32 v0, v156, v188
	v_fmac_f32_e32 v0, v157, v189
	v_fmac_f32_e32 v0, v158, v190
	v_cvt_pk_bf16_f32 v0, v0, v0
	ds_write_b16 v64, v0 offset:15840
	v_fma_f32 v1, v155, v188, v159
	v_fmac_f32_e32 v1, v156, v189
	v_fmac_f32_e32 v1, v157, v190
	v_fmac_f32_e32 v1, v158, v191
	v_cvt_pk_bf16_f32 v1, v1, v1
	ds_write_b16 v64, v1 offset:16368

; __device__ __forceinline__ unsigned cvt_pk_bf16(float lo, float hi) { f32x2_t v = {lo, hi}; bf2_t r = __builtin_convertvector(v, bf2_t); return __builtin_bit_cast(unsigned, r); }
; template <bool FINAL>
; __device__ __forceinline__ void lru_item(const Ctx& C, int l, int item) {
;     ...
;     bf16x8 Bw[2][4][2];
; #pragma unroll
;         for (int ty = 0; ty < 2; ++ty)
; #pragma unroll
;             for (int ks = 0; ks < 2; ++ks) {
;                 const float* wp = (ty ? C.P->in[9] : C.P->in[7]) + ((size_t)((l * 2 + z) * 4 + n) * 64 + 32 * ks + 8 * quad) * 64 + fr;
;                 asm volatile("" : "+v"(wp));
;                 float f[4][8];
; #pragma unroll
;                 for (int dt = 0; dt < 4; ++dt)
; #pragma unroll
;                     for (int e = 0; e < 8; ++e) f[dt][e] = wp[e * 64 + 16 * dt];
; #pragma unroll
;                 for (int dt = 0; dt < 4; ++dt) {
;                     union { bf16x8 v; unsigned u[4]; } t_; t_.u[0] = cvt_pk_bf16(f[dt][0], f[dt][1]); t_.u[1] = cvt_pk_bf16(f[dt][2], f[dt][3]); t_.u[2] = cvt_pk_bf16(f[dt][4], f[dt][5]); t_.u[3] = cvt_pk_bf16(f[dt][6], f[dt][7]); Bw[ty][dt][ks] = t_.v; }
;                 asm volatile("" ::: "memory");
;             }
.LBB0_650:
	v_mov_b64_e32 v[0:1], v[78:79]
	global_load_dword v6, v[0:1], off
	global_load_dword v7, v[0:1], off offset:256
	global_load_dword v8, v[0:1], off offset:64
	global_load_dword v9, v[0:1], off offset:320
	global_load_dword v10, v[0:1], off offset:128
	global_load_dword v11, v[0:1], off offset:384
	global_load_dword v12, v[0:1], off offset:448
	global_load_dword v13, v[0:1], off offset:192
	global_load_dword v20, v[0:1], off offset:512
	global_load_dword v21, v[0:1], off offset:768
	global_load_dword v18, v[0:1], off offset:576
	global_load_dword v19, v[0:1], off offset:832
	global_load_dword v15, v[0:1], off offset:640
	global_load_dword v17, v[0:1], off offset:896
	global_load_dword v14, v[0:1], off offset:960
	global_load_dword v16, v[0:1], off offset:704
	global_load_dword v28, v[0:1], off offset:1024
	global_load_dword v29, v[0:1], off offset:1280
	global_load_dword v26, v[0:1], off offset:1088
	global_load_dword v27, v[0:1], off offset:1344
	global_load_dword v23, v[0:1], off offset:1152
	global_load_dword v25, v[0:1], off offset:1408
	global_load_dword v22, v[0:1], off offset:1472
	global_load_dword v24, v[0:1], off offset:1216
	global_load_dword v37, v[0:1], off offset:1536
	global_load_dword v39, v[0:1], off offset:1792
	global_load_dword v34, v[0:1], off offset:1600
	global_load_dword v35, v[0:1], off offset:1856
	global_load_dword v31, v[0:1], off offset:1664
	global_load_dword v33, v[0:1], off offset:1920
	global_load_dword v30, v[0:1], off offset:1984
	global_load_dword v32, v[0:1], off offset:1728
	v_mov_b64_e32 v[0:1], v[80:81]
	global_load_dword v36, v[0:1], off
	global_load_dword v38, v[0:1], off offset:256
	global_load_dword v40, v[0:1], off offset:64
	global_load_dword v41, v[0:1], off offset:320
	global_load_dword v42, v[0:1], off offset:128
	global_load_dword v43, v[0:1], off offset:384
	global_load_dword v44, v[0:1], off offset:448
	global_load_dword v45, v[0:1], off offset:192
	global_load_dword v52, v[0:1], off offset:512
	global_load_dword v53, v[0:1], off offset:768
	global_load_dword v50, v[0:1], off offset:576
	global_load_dword v51, v[0:1], off offset:832
	global_load_dword v47, v[0:1], off offset:640
	global_load_dword v49, v[0:1], off offset:896
	global_load_dword v46, v[0:1], off offset:960
	global_load_dword v48, v[0:1], off offset:704
	global_load_dword v60, v[0:1], off offset:1024
	global_load_dword v61, v[0:1], off offset:1280
	global_load_dword v58, v[0:1], off offset:1088
	global_load_dword v59, v[0:1], off offset:1344
	global_load_dword v55, v[0:1], off offset:1152
	global_load_dword v57, v[0:1], off offset:1408
	global_load_dword v54, v[0:1], off offset:1472
	global_load_dword v56, v[0:1], off offset:1216
	global_load_dword v71, v[0:1], off offset:1536
	global_load_dword v73, v[0:1], off offset:1792
	global_load_dword v68, v[0:1], off offset:1600
	global_load_dword v69, v[0:1], off offset:1856
	global_load_dword v63, v[0:1], off offset:1664
	global_load_dword v67, v[0:1], off offset:1920
	global_load_dword v62, v[0:1], off offset:1984
	global_load_dword v66, v[0:1], off offset:1728
	v_mov_b64_e32 v[0:1], v[82:83]
	global_load_dword v70, v[0:1], off
	global_load_dword v72, v[0:1], off offset:256
	global_load_dword v74, v[0:1], off offset:64
	global_load_dword v75, v[0:1], off offset:320
	global_load_dword v76, v[0:1], off offset:128
	global_load_dword v77, v[0:1], off offset:384
	global_load_dword v104, v[0:1], off offset:448
	global_load_dword v105, v[0:1], off offset:192
	global_load_dword v174, v[0:1], off offset:512
	global_load_dword v175, v[0:1], off offset:768
	global_load_dword v110, v[0:1], off offset:576
	global_load_dword v111, v[0:1], off offset:832
	global_load_dword v107, v[0:1], off offset:640
	global_load_dword v109, v[0:1], off offset:896
	global_load_dword v106, v[0:1], off offset:960
	global_load_dword v108, v[0:1], off offset:704
	global_load_dword v196, v[0:1], off offset:1024
	global_load_dword v197, v[0:1], off offset:1280
	global_load_dword v194, v[0:1], off offset:1088
	global_load_dword v195, v[0:1], off offset:1344
	global_load_dword v177, v[0:1], off offset:1152
	global_load_dword v193, v[0:1], off offset:1408
	global_load_dword v176, v[0:1], off offset:1472
	global_load_dword v192, v[0:1], off offset:1216
	global_load_dword v205, v[0:1], off offset:1536
	global_load_dword v207, v[0:1], off offset:1792
	global_load_dword v202, v[0:1], off offset:1600
	global_load_dword v203, v[0:1], off offset:1856
	global_load_dword v199, v[0:1], off offset:1664
	global_load_dword v201, v[0:1], off offset:1920
	global_load_dword v198, v[0:1], off offset:1984
	global_load_dword v200, v[0:1], off offset:1728
	v_mov_b64_e32 v[0:1], v[84:85]
	global_load_dword v204, v[0:1], off
	global_load_dword v206, v[0:1], off offset:256
	global_load_dword v208, v[0:1], off offset:64
	global_load_dword v209, v[0:1], off offset:320
	global_load_dword v210, v[0:1], off offset:128
	global_load_dword v211, v[0:1], off offset:384
	global_load_dword v212, v[0:1], off offset:448
	global_load_dword v213, v[0:1], off offset:192
	global_load_dword v232, v[0:1], off offset:512
	global_load_dword v233, v[0:1], off offset:768
	global_load_dword v230, v[0:1], off offset:576
	global_load_dword v231, v[0:1], off offset:832
	global_load_dword v215, v[0:1], off offset:640
	global_load_dword v229, v[0:1], off offset:896
	global_load_dword v214, v[0:1], off offset:960
	global_load_dword v228, v[0:1], off offset:704
	global_load_dword v240, v[0:1], off offset:1024
	global_load_dword v241, v[0:1], off offset:1280
	global_load_dword v238, v[0:1], off offset:1088
	global_load_dword v239, v[0:1], off offset:1344
; __device__ __forceinline__ bf16_t f2bf(float f) { return (bf16_t)(cvt_pk_bf16(f, 0.f) & 0xffffu); }
; __device__ __forceinline__ float bf2f(bf16_t b) { return __uint_as_float(((unsigned)b) << 16); }
; template <bool FINAL>
; __device__ __forceinline__ void lru_item(const Ctx& C, int l, int item) {
;     ...
;     {
;         int ch = tid & 255; asm volatile("" : "+v"(ch)); const int hf = tid >> 8;
;         const float w0 = C.P->in[5][(l * 4 + 0) * 256 + ch], w1 = C.P->in[5][(l * 4 + 1) * 256 + ch], w2 = C.P->in[5][(l * 4 + 2) * 256 + ch], w3 = C.P->in[5][(l * 4 + 3) * 256 + ch], cb = C.P->in[6][l * 256 + ch];
;         const int tl0 = hf * 32, t0 = c * 64 + tl0;
;         const bf16_t* colp = pb + (size_t)(b * SEQ) * 512 + ch;
;         float xm2 = (t0 - 2 >= 0) ? bf2f(colp[(size_t)(t0 - 2) * 512]) : 0.f, xm1 = (t0 - 1 >= 0) ? bf2f(colp[(size_t)(t0 - 1) * 512]) : 0.f, x0 = bf2f(colp[(size_t)t0 * 512]);
; #pragma unroll 1
;         for (int k8 = 0; k8 < 4; ++k8) { float xn[8];
; #pragma unroll
;             for (int k = 0; k < 8; ++k) { const int t = t0 + k8 * 8 + k + 1; xn[k] = (t < SEQ) ? bf2f(colp[(size_t)t * 512]) : 0.f; }
; #pragma unroll
;             for (int k = 0; k < 8; ++k) { xc[(tl0 + k8 * 8 + k) * XCP + ch] = f2bf(cb + w0 * xm2 + w1 * xm1 + w2 * x0 + w3 * xn[k]); xm2 = xm1; xm1 = x0; x0 = xn[k]; } }
	global_load_dword v235, v[0:1], off offset:1152
	global_load_dword v237, v[0:1], off offset:1408
	global_load_dword v234, v[0:1], off offset:1472
	global_load_dword v236, v[0:1], off offset:1216
	global_load_dword v248, v[0:1], off offset:1536
	global_load_dword v249, v[0:1], off offset:1792
	global_load_dword v246, v[0:1], off offset:1600
	global_load_dword v247, v[0:1], off offset:1856
	global_load_dword v243, v[0:1], off offset:1664
	global_load_dword v245, v[0:1], off offset:1920
	global_load_dword v242, v[0:1], off offset:1984
	global_load_dword v244, v[0:1], off offset:1728
	v_mov_b32_e32 v4, v99
	v_readlane_b32 s0, v254, 63
	v_readlane_b32 s78, v251, 14
	v_readlane_b32 s79, v251, 15
	v_readlane_b32 s80, v251, 16
	v_readlane_b32 s81, v251, 17
	v_add_u32_e32 v0, s0, v4
	v_ashrrev_i32_e32 v1, 31, v0
	v_lshl_add_u64 v[2:3], v[0:1], 2, s[78:79]
	v_add_u32_e32 v0, s40, v0
	global_load_dword v162, v[2:3], off
	global_load_dword v163, v[2:3], off offset:1024
	global_load_dword v164, v[2:3], off offset:2048
	global_load_dword v165, v[2:3], off offset:3072
	v_ashrrev_i32_e32 v1, 31, v0
	v_lshl_add_u64 v[0:1], v[0:1], 2, s[80:81]
	global_load_dword v166, v[0:1], off
	s_lshl_b32 s0, s48, 6
	s_and_b32 s0, s0, 0xfffff000
	s_ashr_i32 s1, s0, 31
	s_and_b32 s51, s48, 63
	s_lshl_b64 s[0:1], s[0:1], 10
	s_add_u32 s0, s10, s0
	s_addc_u32 s1, s11, s1
	v_lshl_add_u32 v183, s51, 6, v86
	v_ashrrev_i32_e32 v5, 31, v4
	v_lshl_add_u64 v[0:1], v[4:5], 1, s[0:1]
	v_lshl_add_u32 v64, v4, 1, v142
	s_and_b32 s0, s47, 63
	s_lshl_b32 s49, s0, 6
	s_and_b32 s8, s46, 0xfffff000
	s_mov_b32 s66, 0x358637bd
	s_mov_b64 s[22:23], 0x1000
	s_mov_b64 s[30:31], 0x2000
	v_add_u32_e32 v2, 2, v183
	v_mov_b32_e32 v3, 0
	v_lshlrev_b64 v[2:3], 10, v[2:3]
	v_lshl_add_u64 v[2:3], v[2:3], 0, v[0:1]
	global_load_ushort v4, v[2:3], off offset:-4096
	global_load_ushort v5, v[2:3], off offset:-3072
	global_load_ushort v167, v[2:3], off offset:-2048
	global_load_ushort v168, v[2:3], off offset:-1024
	global_load_ushort v169, v[2:3], off
	global_load_ushort v170, v[2:3], off offset:1024
	global_load_ushort v171, v[2:3], off offset:2048
	global_load_ushort v172, v[2:3], off offset:3072
	v_lshl_add_u64 v[2:3], v[2:3], 0, s[30:31]
	global_load_ushort v173, v[2:3], off offset:-4096
	global_load_ushort v178, v[2:3], off offset:-3072
	global_load_ushort v179, v[2:3], off offset:-2048
	global_load_ushort v180, v[2:3], off offset:-1024
	global_load_ushort v181, v[2:3], off
	global_load_ushort v188, v[2:3], off offset:1024
	global_load_ushort v189, v[2:3], off offset:2048
	global_load_ushort v190, v[2:3], off offset:3072
	v_lshl_add_u64 v[2:3], v[2:3], 0, s[30:31]
	global_load_ushort v191, v[2:3], off offset:-4096
	global_load_ushort v223, v[2:3], off offset:-3072
	global_load_ushort v250, v[2:3], off offset:-2048
	s_movk_i32 s9, 0xfe0
	v_cmp_eq_u32_e32 vcc, 0, v183
	v_cmp_eq_u32_e64 s[0:1], s9, v183
	s_waitcnt vmcnt(0)
	v_cndmask_b32_e64 v4, v4, 0, vcc
	v_cndmask_b32_e64 v5, v5, 0, vcc
	v_lshlrev_b32_e32 v4, 16, v4
	v_lshlrev_b32_e32 v5, 16, v5
	v_lshlrev_b32_e32 v167, 16, v167
	v_lshlrev_b32_e32 v168, 16, v168
	v_lshlrev_b32_e32 v169, 16, v169
	v_lshlrev_b32_e32 v170, 16, v170
	v_lshlrev_b32_e32 v171, 16, v171
	v_lshlrev_b32_e32 v172, 16, v172
	v_lshlrev_b32_e32 v173, 16, v173
	v_lshlrev_b32_e32 v178, 16, v178
	v_lshlrev_b32_e32 v179, 16, v179
	v_lshlrev_b32_e32 v180, 16, v180
	v_lshlrev_b32_e32 v181, 16, v181
	v_lshlrev_b32_e32 v188, 16, v188
	v_lshlrev_b32_e32 v189, 16, v189
	v_lshlrev_b32_e32 v190, 16, v190
	v_lshlrev_b32_e32 v191, 16, v191
	v_lshlrev_b32_e32 v223, 16, v223
	v_lshlrev_b32_e32 v250, 16, v250
	v_fma_f32 v0, v162, v4, v166
	v_fmac_f32_e32 v0, v163, v5
	v_fmac_f32_e32 v0, v164, v167
	v_fmac_f32_e32 v0, v165, v168
	v_cvt_pk_bf16_f32 v0, v0, v0
	ds_write_b16 v64, v0
	v_fma_f32 v1, v162, v5, v166
	v_fmac_f32_e32 v1, v163, v167
	v_fmac_f32_e32 v1, v164, v168
	v_fmac_f32_e32 v1, v165, v169
	v_cvt_pk_bf16_f32 v1, v1, v1
	ds_write_b16 v64, v1 offset:528
	v_fma_f32 v0, v162, v167, v166
	v_fmac_f32_e32 v0, v163, v168
	v_fmac_f32_e32 v0, v164, v169
	v_fmac_f32_e32 v0, v165, v170
	v_cvt_pk_bf16_f32 v0, v0, v0
	ds_write_b16 v64, v0 offset:1056
	v_fma_f32 v1, v162, v168, v166
	v_fmac_f32_e32 v1, v163, v169
	v_fmac_f32_e32 v1, v164, v170
	v_fmac_f32_e32 v1, v165, v171
	v_cvt_pk_bf16_f32 v1, v1, v1
	ds_write_b16 v64, v1 offset:1584
	v_fma_f32 v0, v162, v169, v166
	v_fmac_f32_e32 v0, v163, v170
	v_fmac_f32_e32 v0, v164, v171
	v_fmac_f32_e32 v0, v165, v172
	v_cvt_pk_bf16_f32 v0, v0, v0
	ds_write_b16 v64, v0 offset:2112
	v_fma_f32 v1, v162, v170, v166
	v_fmac_f32_e32 v1, v163, v171
	v_fmac_f32_e32 v1, v164, v172
	v_fmac_f32_e32 v1, v165, v173
	v_cvt_pk_bf16_f32 v1, v1, v1
	ds_write_b16 v64, v1 offset:2640
	v_fma_f32 v0, v162, v171, v166
	v_fmac_f32_e32 v0, v163, v172
	v_fmac_f32_e32 v0, v164, v173
	v_fmac_f32_e32 v0, v165, v178
	v_cvt_pk_bf16_f32 v0, v0, v0
	ds_write_b16 v64, v0 offset:3168
	v_fma_f32 v1, v162, v172, v166
	v_fmac_f32_e32 v1, v163, v173
	v_fmac_f32_e32 v1, v164, v178
	v_fmac_f32_e32 v1, v165, v179
	v_cvt_pk_bf16_f32 v1, v1, v1
	ds_write_b16 v64, v1 offset:3696
	v_fma_f32 v0, v162, v173, v166
	v_fmac_f32_e32 v0, v163, v178
	v_fmac_f32_e32 v0, v164, v179
	v_fmac_f32_e32 v0, v165, v180
	v_cvt_pk_bf16_f32 v0, v0, v0
	ds_write_b16 v64, v0 offset:4224
	v_fma_f32 v1, v162, v178, v166
	v_fmac_f32_e32 v1, v163, v179
	v_fmac_f32_e32 v1, v164, v180
	v_fmac_f32_e32 v1, v165, v181
	v_cvt_pk_bf16_f32 v1, v1, v1
	ds_write_b16 v64, v1 offset:4752
	v_fma_f32 v0, v162, v179, v166
	v_fmac_f32_e32 v0, v163, v180
; __device__ __forceinline__ bf16_t f2bf(float f) { return (bf16_t)(cvt_pk_bf16(f, 0.f) & 0xffffu); }
; __device__ __forceinline__ float bf2f(bf16_t b) { return __uint_as_float(((unsigned)b) << 16); }
; template <bool FINAL>
; __device__ __forceinline__ void lru_item(const Ctx& C, int l, int item) {
;     ...
; #pragma unroll 1
;         for (int k8 = 0; k8 < 4; ++k8) { float xn[8];
; #pragma unroll
;             for (int k = 0; k < 8; ++k) { const int t = t0 + k8 * 8 + k + 1; xn[k] = (t < SEQ) ? bf2f(colp[(size_t)t * 512]) : 0.f; }
; #pragma unroll
;             for (int k = 0; k < 8; ++k) { xc[(tl0 + k8 * 8 + k) * XCP + ch] = f2bf(cb + w0 * xm2 + w1 * xm1 + w2 * x0 + w3 * xn[k]); xm2 = xm1; xm1 = x0; x0 = xn[k]; } }
	v_fmac_f32_e32 v0, v164, v181
	v_fmac_f32_e32 v0, v165, v188
	v_cvt_pk_bf16_f32 v0, v0, v0
	ds_write_b16 v64, v0 offset:5280
	v_fma_f32 v1, v162, v180, v166
	v_fmac_f32_e32 v1, v163, v181
	v_fmac_f32_e32 v1, v164, v188
	v_fmac_f32_e32 v1, v165, v189
	v_cvt_pk_bf16_f32 v1, v1, v1
	ds_write_b16 v64, v1 offset:5808
	v_fma_f32 v0, v162, v181, v166
	v_fmac_f32_e32 v0, v163, v188
	v_fmac_f32_e32 v0, v164, v189
	v_fmac_f32_e32 v0, v165, v190
	v_cvt_pk_bf16_f32 v0, v0, v0
	ds_write_b16 v64, v0 offset:6336
	v_fma_f32 v1, v162, v188, v166
	v_fmac_f32_e32 v1, v163, v189
	v_fmac_f32_e32 v1, v164, v190
	v_fmac_f32_e32 v1, v165, v191
	v_cvt_pk_bf16_f32 v1, v1, v1
	ds_write_b16 v64, v1 offset:6864
	v_fma_f32 v0, v162, v189, v166
	v_fmac_f32_e32 v0, v163, v190
	v_fmac_f32_e32 v0, v164, v191
	v_fmac_f32_e32 v0, v165, v223
	v_cvt_pk_bf16_f32 v0, v0, v0
	ds_write_b16 v64, v0 offset:7392
	v_fma_f32 v1, v162, v190, v166
	v_fmac_f32_e32 v1, v163, v191
	v_fmac_f32_e32 v1, v164, v223
	v_fmac_f32_e32 v1, v165, v250
	v_cvt_pk_bf16_f32 v1, v1, v1
	ds_write_b16 v64, v1 offset:7920
	global_load_ushort v4, v[2:3], off offset:-1024
	global_load_ushort v5, v[2:3], off
	global_load_ushort v167, v[2:3], off offset:1024
	global_load_ushort v168, v[2:3], off offset:2048
	global_load_ushort v169, v[2:3], off offset:3072
	v_lshl_add_u64 v[2:3], v[2:3], 0, s[30:31]
	global_load_ushort v170, v[2:3], off offset:-4096
	global_load_ushort v171, v[2:3], off offset:-3072
	global_load_ushort v172, v[2:3], off offset:-2048
	global_load_ushort v173, v[2:3], off offset:-1024
	global_load_ushort v178, v[2:3], off
	global_load_ushort v179, v[2:3], off offset:1024
	global_load_ushort v180, v[2:3], off offset:2048
	global_load_ushort v181, v[2:3], off offset:3072
	v_lshl_add_u64 v[2:3], v[2:3], 0, s[30:31]
	global_load_ushort v188, v[2:3], off offset:-4096
	global_load_ushort v189, v[2:3], off offset:-3072
	global_load_ushort v190, v[2:3], off offset:-2048
	s_waitcnt vmcnt(0)
	v_cndmask_b32_e64 v190, v190, 0, s[0:1]
	v_lshlrev_b32_e32 v4, 16, v4
	v_lshlrev_b32_e32 v5, 16, v5
	v_lshlrev_b32_e32 v167, 16, v167
	v_lshlrev_b32_e32 v168, 16, v168
	v_lshlrev_b32_e32 v169, 16, v169
	v_lshlrev_b32_e32 v170, 16, v170
	v_lshlrev_b32_e32 v171, 16, v171
	v_lshlrev_b32_e32 v172, 16, v172
	v_lshlrev_b32_e32 v173, 16, v173
	v_lshlrev_b32_e32 v178, 16, v178
	v_lshlrev_b32_e32 v179, 16, v179
	v_lshlrev_b32_e32 v180, 16, v180
	v_lshlrev_b32_e32 v181, 16, v181
	v_lshlrev_b32_e32 v188, 16, v188
	v_lshlrev_b32_e32 v189, 16, v189
	v_lshlrev_b32_e32 v190, 16, v190
	v_fma_f32 v0, v162, v191, v166
	v_fmac_f32_e32 v0, v163, v223
	v_fmac_f32_e32 v0, v164, v250
	v_fmac_f32_e32 v0, v165, v4
	v_cvt_pk_bf16_f32 v0, v0, v0
	ds_write_b16 v64, v0 offset:8448
	v_fma_f32 v1, v162, v223, v166
	v_fmac_f32_e32 v1, v163, v250
	v_fmac_f32_e32 v1, v164, v4
	v_fmac_f32_e32 v1, v165, v5
	v_cvt_pk_bf16_f32 v1, v1, v1
	ds_write_b16 v64, v1 offset:8976
	v_fma_f32 v0, v162, v250, v166
	v_fmac_f32_e32 v0, v163, v4
	v_fmac_f32_e32 v0, v164, v5
	v_fmac_f32_e32 v0, v165, v167
	v_cvt_pk_bf16_f32 v0, v0, v0
	ds_write_b16 v64, v0 offset:9504
	v_fma_f32 v1, v162, v4, v166
	v_fmac_f32_e32 v1, v163, v5
	v_fmac_f32_e32 v1, v164, v167
	v_fmac_f32_e32 v1, v165, v168
	v_cvt_pk_bf16_f32 v1, v1, v1
	ds_write_b16 v64, v1 offset:10032
	v_fma_f32 v0, v162, v5, v166
	v_fmac_f32_e32 v0, v163, v167
	v_fmac_f32_e32 v0, v164, v168
	v_fmac_f32_e32 v0, v165, v169
	v_cvt_pk_bf16_f32 v0, v0, v0
	ds_write_b16 v64, v0 offset:10560
	v_fma_f32 v1, v162, v167, v166
	v_fmac_f32_e32 v1, v163, v168
	v_fmac_f32_e32 v1, v164, v169
	v_fmac_f32_e32 v1, v165, v170
	v_cvt_pk_bf16_f32 v1, v1, v1
	ds_write_b16 v64, v1 offset:11088
	v_fma_f32 v0, v162, v168, v166
	v_fmac_f32_e32 v0, v163, v169
	v_fmac_f32_e32 v0, v164, v170
	v_fmac_f32_e32 v0, v165, v171
	v_cvt_pk_bf16_f32 v0, v0, v0
	ds_write_b16 v64, v0 offset:11616
	v_fma_f32 v1, v162, v169, v166
	v_fmac_f32_e32 v1, v163, v170
	v_fmac_f32_e32 v1, v164, v171
	v_fmac_f32_e32 v1, v165, v172
	v_cvt_pk_bf16_f32 v1, v1, v1
	ds_write_b16 v64, v1 offset:12144
	v_fma_f32 v0, v162, v170, v166
	v_fmac_f32_e32 v0, v163, v171
	v_fmac_f32_e32 v0, v164, v172
	v_fmac_f32_e32 v0, v165, v173
	v_cvt_pk_bf16_f32 v0, v0, v0
	ds_write_b16 v64, v0 offset:12672
	v_fma_f32 v1, v162, v171, v166
	v_fmac_f32_e32 v1, v163, v172
	v_fmac_f32_e32 v1, v164, v173
	v_fmac_f32_e32 v1, v165, v178
	v_cvt_pk_bf16_f32 v1, v1, v1
	ds_write_b16 v64, v1 offset:13200
	v_fma_f32 v0, v162, v172, v166
	v_fmac_f32_e32 v0, v163, v173
	v_fmac_f32_e32 v0, v164, v178
	v_fmac_f32_e32 v0, v165, v179
	v_cvt_pk_bf16_f32 v0, v0, v0
	ds_write_b16 v64, v0 offset:13728
	v_fma_f32 v1, v162, v173, v166
	v_fmac_f32_e32 v1, v163, v178
	v_fmac_f32_e32 v1, v164, v179
	v_fmac_f32_e32 v1, v165, v180
	v_cvt_pk_bf16_f32 v1, v1, v1
	ds_write_b16 v64, v1 offset:14256
	v_fma_f32 v0, v162, v178, v166
	v_fmac_f32_e32 v0, v163, v179
	v_fmac_f32_e32 v0, v164, v180
	v_fmac_f32_e32 v0, v165, v181
	v_cvt_pk_bf16_f32 v0, v0, v0
	ds_write_b16 v64, v0 offset:14784
	v_fma_f32 v1, v162, v179, v166
	v_fmac_f32_e32 v1, v163, v180
	v_fmac_f32_e32 v1, v164, v181
	v_fmac_f32_e32 v1, v165, v188
	v_cvt_pk_bf16_f32 v1, v1, v1
	ds_write_b16 v64, v1 offset:15312
	v_fma_f32 v0, v162, v180, v166
	v_fmac_f32_e32 v0, v163, v181
	v_fmac_f32_e32 v0, v164, v188
	v_fmac_f32_e32 v0, v165, v189
	v_cvt_pk_bf16_f32 v0, v0, v0
	ds_write_b16 v64, v0 offset:15840
	v_fma_f32 v1, v162, v181, v166
	v_fmac_f32_e32 v1, v163, v188
	v_fmac_f32_e32 v1, v164, v189
	v_fmac_f32_e32 v1, v165, v190
	v_cvt_pk_bf16_f32 v1, v1, v1
	ds_write_b16 v64, v1 offset:16368
